# speedup vs baseline: 1.0069x; 1.0069x over previous
.LBB0_86:
	s_mov_b32 s23, s10
	s_mov_b32 s10, s20
	s_add_i32 s24, s33, 2
	s_add_i32 s25, s10, 0
	v_add_u32_e32 v210, s25, v207
	v_mfma_f32_32x32x16_bf16 v[112:127], v[100:103], v[130:133], 0
	v_add_f32_e32 v100, 0, v80
	v_add_f32_e32 v101, 0, v81
	v_add_f32_e32 v100, v82, v100
	v_add_f32_e32 v101, v83, v101
	v_cvt_pk_bf16_f32 v158, v80, v81
	v_cvt_pk_bf16_f32 v159, v82, v83
	v_add_f32_e32 v80, v84, v100
	v_add_f32_e32 v81, v85, v101
	v_add_f32_e32 v146, v86, v80
	v_cvt_pk_bf16_f32 v160, v84, v85
	v_mfma_f32_32x32x16_bf16 v[96:111], v[96:99], v[130:133], 0
	v_add_f32_e32 v84, v87, v81
	v_cvt_pk_bf16_f32 v161, v86, v87
	ds_read_b64_tr_b16 v[80:81], v210 offset:49152
	ds_read_b64_tr_b16 v[82:83], v210 offset:49664
	v_add_f32_e32 v85, v88, v146
	v_add_f32_e32 v84, v89, v84
	v_mfma_f32_32x32x16_bf16 v[112:127], v[182:185], v[134:137], v[112:127]
	v_add_f32_e32 v146, v90, v85
	v_add_f32_e32 v147, v91, v84
	v_cvt_pk_bf16_f32 v154, v88, v89
	v_cvt_pk_bf16_f32 v155, v90, v91
	ds_read_b64_tr_b16 v[84:85], v210 offset:53248
	ds_read_b64_tr_b16 v[86:87], v210 offset:53760
	v_add_f32_e32 v88, v92, v146
	v_add_f32_e32 v89, v93, v147
	v_mfma_f32_32x32x16_bf16 v[96:111], v[178:181], v[134:137], v[96:111]
	v_add_f32_e32 v146, v94, v88
	v_add_f32_e32 v147, v95, v89
	v_cvt_pk_bf16_f32 v156, v92, v93
	v_cvt_pk_bf16_f32 v157, v94, v95
	ds_read_b64_tr_b16 v[88:89], v210 offset:57344
	ds_read_b64_tr_b16 v[90:91], v210 offset:57856
	v_add_f32_e32 v92, v64, v146
	v_add_f32_e32 v93, v65, v147
	v_mfma_f32_32x32x16_bf16 v[112:127], v[174:177], v[138:141], v[112:127]
	v_add_f32_e32 v92, v66, v92
	v_add_f32_e32 v93, v67, v93
	v_cvt_pk_bf16_f32 v150, v64, v65
	v_cvt_pk_bf16_f32 v151, v66, v67
	ds_read_b64_tr_b16 v[64:65], v210 offset:61440
	ds_read_b64_tr_b16 v[66:67], v210 offset:61952
	v_add_f32_e32 v92, v68, v92
	v_add_f32_e32 v93, v69, v93
	v_mfma_f32_32x32x16_bf16 v[96:111], v[170:173], v[138:141], v[96:111]
	v_add_f32_e32 v92, v70, v92
	v_add_f32_e32 v93, v71, v93
	v_cvt_pk_bf16_f32 v152, v68, v69
	v_cvt_pk_bf16_f32 v153, v70, v71
	v_add_f32_e32 v68, v72, v92
	v_add_f32_e32 v69, v73, v93
	v_mfma_f32_32x32x16_bf16 v[112:127], v[166:169], v[142:145], v[112:127]
	v_add_f32_e32 v68, v74, v68
	v_add_f32_e32 v69, v75, v69
	v_cvt_pk_bf16_f32 v146, v72, v73
	v_cvt_pk_bf16_f32 v147, v74, v75
	v_add_f32_e32 v68, v76, v68
	v_add_f32_e32 v69, v77, v69
	v_mfma_f32_32x32x16_bf16 v[96:111], v[162:165], v[142:145], v[96:111]
	v_add_f32_e32 v68, v78, v68
	v_add_f32_e32 v69, v79, v69
	v_cvt_pk_bf16_f32 v148, v76, v77
	v_cvt_pk_bf16_f32 v149, v78, v79
	s_nop 0
	v_exp_f32_e32 v112, v112
	v_exp_f32_e32 v113, v113
	s_waitcnt lgkmcnt(4)
	v_mfma_f32_32x32x16_bf16 v[48:63], v[80:83], v[158:161], v[48:63]
	v_add_f32_e32 v92, v68, v69
	ds_read_b64_tr_b16 v[68:69], v210 offset:50176
	ds_read_b64_tr_b16 v[70:71], v210 offset:50688
	v_exp_f32_e32 v114, v114
	v_exp_f32_e32 v115, v115
	v_mfma_f32_32x32x16_bf16 v[32:47], v[84:87], v[158:161], v[32:47]
	ds_read_b64_tr_b16 v[72:73], v210 offset:54272
	ds_read_b64_tr_b16 v[74:75], v210 offset:54784
	v_exp_f32_e32 v116, v116
	v_exp_f32_e32 v117, v117
	s_waitcnt lgkmcnt(4)
	v_mfma_f32_32x32x16_bf16 v[16:31], v[88:91], v[158:161], v[16:31]
	s_add_i32 s44, s33, 4
	s_min_u32 s44, s44, s19
	s_mul_i32 s90, s44, 0x160000
	s_add_i32 s44, s23, s5
	v_lshl_add_u64 v[212:213], v[198:199], 0, s[90:91]
	s_mov_b32 m0, s44
	v_lshl_add_u64 v[214:215], v[212:213], 0, s[72:73]
	global_load_lds_dwordx4 v[214:215], off
	ds_read_b64_tr_b16 v[76:77], v210 offset:58368
	ds_read_b64_tr_b16 v[78:79], v210 offset:58880
	v_exp_f32_e32 v118, v118
	v_exp_f32_e32 v119, v119
	v_mfma_f32_32x32x16_bf16 v[0:15], v[64:67], v[158:161], v[0:15]
	ds_read_b64_tr_b16 v[80:81], v210 offset:62464
	ds_read_b64_tr_b16 v[82:83], v210 offset:62976
	v_exp_f32_e32 v120, v120
	v_exp_f32_e32 v121, v121
	s_waitcnt lgkmcnt(4)
	v_mfma_f32_32x32x16_bf16 v[48:63], v[68:71], v[154:157], v[48:63]
	v_add_u32_e32 v64, s11, v204
	ds_read_b64_tr_b16 v[84:85], v210 offset:51200
	ds_read_b64_tr_b16 v[86:87], v210 offset:51712
	ds_read_b128 v[68:71], v64
	v_exp_f32_e32 v122, v122
	v_exp_f32_e32 v123, v123
	v_mfma_f32_32x32x16_bf16 v[32:47], v[72:75], v[154:157], v[32:47]
	ds_read_b64_tr_b16 v[72:73], v210 offset:55296
	ds_read_b64_tr_b16 v[74:75], v210 offset:55808
	ds_read_b128 v[64:67], v64 offset:4096
	v_exp_f32_e32 v124, v124
	v_exp_f32_e32 v125, v125
	s_waitcnt lgkmcnt(6)
	v_mfma_f32_32x32x16_bf16 v[16:31], v[76:79], v[154:157], v[16:31]
	s_add_i32 s44, s23, s21
	s_mov_b32 m0, s44
	v_lshl_add_u64 v[212:213], v[212:213], 0, s[94:95]
	global_load_lds_dwordx4 v[212:213], off
	v_add_u32_e32 v88, s11, v128
	ds_read_b64_tr_b16 v[76:77], v210 offset:59392
	ds_read_b64_tr_b16 v[78:79], v210 offset:59904
	ds_read_b128 v[182:185], v88
	v_exp_f32_e32 v126, v126
	v_exp_f32_e32 v127, v127
	v_mfma_f32_32x32x16_bf16 v[0:15], v[80:83], v[154:157], v[0:15]
	ds_read_b64_tr_b16 v[80:81], v210 offset:63488
	ds_read_b64_tr_b16 v[82:83], v210 offset:64000
	ds_read_b128 v[178:181], v88 offset:4096
	v_exp_f32_e32 v96, v96
	v_exp_f32_e32 v97, v97
	s_waitcnt lgkmcnt(7)
	v_mfma_f32_32x32x16_bf16 v[48:63], v[84:87], v[150:153], v[48:63]
	v_add_u32_e32 v88, s11, v205
	ds_read_b64_tr_b16 v[84:85], v210 offset:52224
	ds_read_b64_tr_b16 v[86:87], v210 offset:52736
	ds_read_b128 v[174:177], v88
	v_exp_f32_e32 v98, v98
	v_exp_f32_e32 v99, v99
	v_mfma_f32_32x32x16_bf16 v[32:47], v[72:75], v[150:153], v[32:47]
	ds_read_b64_tr_b16 v[72:73], v210 offset:56320
	ds_read_b64_tr_b16 v[74:75], v210 offset:56832
	ds_read_b128 v[170:173], v88 offset:4096
	v_exp_f32_e32 v100, v100
	v_exp_f32_e32 v101, v101
	s_waitcnt lgkmcnt(7)
	v_mfma_f32_32x32x16_bf16 v[16:31], v[76:79], v[150:153], v[16:31]
	s_min_u32 s44, s24, s19
	s_mul_i32 s90, s44, 0x160000
	s_add_i32 s44, s11, s22
	s_mov_b32 m0, s44
	v_lshl_add_u64 v[212:213], v[200:201], 0, s[90:91]
	global_load_lds_dwordx4 v[212:213], off
	v_add_u32_e32 v88, s11, v206
	ds_read_b64_tr_b16 v[76:77], v210 offset:60416
	ds_read_b64_tr_b16 v[78:79], v210 offset:60928
	ds_read_b128 v[166:169], v88
	v_exp_f32_e32 v102, v102
	v_exp_f32_e32 v103, v103
	v_mfma_f32_32x32x16_bf16 v[0:15], v[80:83], v[150:153], v[0:15]
	ds_read_b64_tr_b16 v[80:81], v210 offset:64512
	ds_read_b64_tr_b16 v[82:83], v210 offset:65024
	ds_read_b128 v[162:165], v88 offset:4096
	v_exp_f32_e32 v104, v104
	v_exp_f32_e32 v105, v105
	s_waitcnt lgkmcnt(7)
	v_mfma_f32_32x32x16_bf16 v[48:63], v[84:87], v[146:149], v[48:63]
	v_exp_f32_e32 v106, v106
	v_exp_f32_e32 v107, v107
	v_mfma_f32_32x32x16_bf16 v[32:47], v[72:75], v[146:149], v[32:47]
	v_exp_f32_e32 v108, v108
	v_exp_f32_e32 v109, v109
	s_waitcnt lgkmcnt(1)
	v_mfma_f32_32x32x16_bf16 v[16:31], v[76:79], v[146:149], v[16:31]
	s_addk_i32 s44, 0x400
	s_mov_b32 m0, s44
	v_lshl_add_u64 v[212:213], v[212:213], 0, s[26:27]
	global_load_lds_dwordx4 v[212:213], off
	v_exp_f32_e32 v110, v110
	v_exp_f32_e32 v111, v111
	v_mfma_f32_32x32x16_bf16 v[0:15], v[80:83], v[146:149], v[0:15]
	s_waitcnt vmcnt(4) lgkmcnt(0)
	s_barrier
	v_add_f32_e32 v186, v209, v92
	v_add_u32_e32 v210, s23, v208
	v_mfma_f32_32x32x16_bf16 v[80:95], v[68:71], v[130:133], 0
	v_add_f32_e32 v68, 0, v112
	v_add_f32_e32 v69, 0, v113
	v_add_f32_e32 v68, v114, v68
	v_add_f32_e32 v69, v115, v69
	v_cvt_pk_bf16_f32 v158, v112, v113
	v_cvt_pk_bf16_f32 v159, v114, v115
	v_add_f32_e32 v68, v116, v68
	v_add_f32_e32 v112, v117, v69
	v_add_f32_e32 v146, v118, v68
	v_cvt_pk_bf16_f32 v160, v116, v117
	v_mfma_f32_32x32x16_bf16 v[64:79], v[64:67], v[130:133], 0
	v_add_f32_e32 v116, v119, v112
	v_cvt_pk_bf16_f32 v161, v118, v119
	ds_read_b64_tr_b16 v[112:113], v210 offset:49152
	ds_read_b64_tr_b16 v[114:115], v210 offset:49664
	v_add_f32_e32 v117, v120, v146
	v_add_f32_e32 v116, v121, v116
	v_mfma_f32_32x32x16_bf16 v[80:95], v[182:185], v[134:137], v[80:95]
	v_add_f32_e32 v146, v122, v117
	v_add_f32_e32 v147, v123, v116
	v_cvt_pk_bf16_f32 v154, v120, v121
	v_cvt_pk_bf16_f32 v155, v122, v123
	ds_read_b64_tr_b16 v[116:117], v210 offset:53248
	ds_read_b64_tr_b16 v[118:119], v210 offset:53760
	v_add_f32_e32 v120, v124, v146
	v_add_f32_e32 v121, v125, v147
	v_mfma_f32_32x32x16_bf16 v[64:79], v[178:181], v[134:137], v[64:79]
	v_add_f32_e32 v146, v126, v120
	v_add_f32_e32 v147, v127, v121
	v_cvt_pk_bf16_f32 v156, v124, v125
	v_cvt_pk_bf16_f32 v157, v126, v127
	ds_read_b64_tr_b16 v[120:121], v210 offset:57344
	ds_read_b64_tr_b16 v[122:123], v210 offset:57856
	v_add_f32_e32 v124, v96, v146
	v_add_f32_e32 v125, v97, v147
	v_mfma_f32_32x32x16_bf16 v[80:95], v[174:177], v[138:141], v[80:95]
	v_add_f32_e32 v124, v98, v124
	v_add_f32_e32 v125, v99, v125
	v_cvt_pk_bf16_f32 v150, v96, v97
	v_cvt_pk_bf16_f32 v151, v98, v99
	ds_read_b64_tr_b16 v[96:97], v210 offset:61440
	ds_read_b64_tr_b16 v[98:99], v210 offset:61952
	v_add_f32_e32 v124, v100, v124
	v_add_f32_e32 v125, v101, v125
	v_mfma_f32_32x32x16_bf16 v[64:79], v[170:173], v[138:141], v[64:79]
	v_add_f32_e32 v124, v102, v124
	v_add_f32_e32 v125, v103, v125
	v_cvt_pk_bf16_f32 v152, v100, v101
	v_cvt_pk_bf16_f32 v153, v102, v103
	v_add_f32_e32 v100, v104, v124
	v_add_f32_e32 v101, v105, v125
	v_mfma_f32_32x32x16_bf16 v[80:95], v[166:169], v[142:145], v[80:95]
	v_add_f32_e32 v100, v106, v100
	v_add_f32_e32 v101, v107, v101
	v_cvt_pk_bf16_f32 v146, v104, v105
	v_cvt_pk_bf16_f32 v147, v106, v107
	v_add_f32_e32 v100, v108, v100
	v_add_f32_e32 v101, v109, v101
	v_mfma_f32_32x32x16_bf16 v[64:79], v[162:165], v[142:145], v[64:79]
	v_add_f32_e32 v100, v110, v100
	v_add_f32_e32 v101, v111, v101
	v_cvt_pk_bf16_f32 v148, v108, v109
	v_cvt_pk_bf16_f32 v149, v110, v111
	v_add_f32_e32 v100, v100, v101
	v_exp_f32_e32 v80, v80
	v_exp_f32_e32 v81, v81
	s_waitcnt lgkmcnt(4)
	v_mfma_f32_32x32x16_bf16 v[48:63], v[112:115], v[158:161], v[48:63]
	v_add_f32_e32 v209, v186, v100
	ds_read_b64_tr_b16 v[100:101], v210 offset:50176
	ds_read_b64_tr_b16 v[102:103], v210 offset:50688
	v_exp_f32_e32 v82, v82
	v_exp_f32_e32 v83, v83
	v_mfma_f32_32x32x16_bf16 v[32:47], v[116:119], v[158:161], v[32:47]
	ds_read_b64_tr_b16 v[104:105], v210 offset:54272
	ds_read_b64_tr_b16 v[106:107], v210 offset:54784
	v_exp_f32_e32 v84, v84
	v_exp_f32_e32 v85, v85
	s_waitcnt lgkmcnt(4)
	v_mfma_f32_32x32x16_bf16 v[16:31], v[120:123], v[158:161], v[16:31]
	s_add_i32 s44, s33, 5
	s_min_u32 s44, s44, s19
	s_mul_i32 s90, s44, 0x160000
	s_add_i32 s44, s11, s5
	v_lshl_add_u64 v[212:213], v[198:199], 0, s[90:91]
	s_mov_b32 m0, s44
	v_lshl_add_u64 v[214:215], v[212:213], 0, s[72:73]
	global_load_lds_dwordx4 v[214:215], off
	ds_read_b64_tr_b16 v[108:109], v210 offset:58368
	ds_read_b64_tr_b16 v[110:111], v210 offset:58880
	v_exp_f32_e32 v86, v86
	v_exp_f32_e32 v87, v87
	v_mfma_f32_32x32x16_bf16 v[0:15], v[96:99], v[158:161], v[0:15]
	ds_read_b64_tr_b16 v[112:113], v210 offset:62464
	ds_read_b64_tr_b16 v[114:115], v210 offset:62976
	v_exp_f32_e32 v88, v88
	v_exp_f32_e32 v89, v89
	s_waitcnt lgkmcnt(4)
	v_mfma_f32_32x32x16_bf16 v[48:63], v[100:103], v[154:157], v[48:63]
	v_add_u32_e32 v96, s25, v204
	ds_read_b64_tr_b16 v[116:117], v210 offset:51200
	ds_read_b64_tr_b16 v[118:119], v210 offset:51712
	ds_read_b128 v[100:103], v96
	v_exp_f32_e32 v90, v90
	v_exp_f32_e32 v91, v91
	v_mfma_f32_32x32x16_bf16 v[32:47], v[104:107], v[154:157], v[32:47]
	ds_read_b64_tr_b16 v[104:105], v210 offset:55296
	ds_read_b64_tr_b16 v[106:107], v210 offset:55808
	ds_read_b128 v[96:99], v96 offset:4096
	v_exp_f32_e32 v92, v92
	v_exp_f32_e32 v93, v93
	s_waitcnt lgkmcnt(6)
	v_mfma_f32_32x32x16_bf16 v[16:31], v[108:111], v[154:157], v[16:31]
	s_add_i32 s44, s11, s21
	s_mov_b32 m0, s44
	v_lshl_add_u64 v[212:213], v[212:213], 0, s[94:95]
	global_load_lds_dwordx4 v[212:213], off
	v_add_u32_e32 v120, s25, v128
	ds_read_b64_tr_b16 v[108:109], v210 offset:59392
	ds_read_b64_tr_b16 v[110:111], v210 offset:59904
	ds_read_b128 v[182:185], v120
	v_exp_f32_e32 v94, v94
	v_exp_f32_e32 v95, v95
	v_mfma_f32_32x32x16_bf16 v[0:15], v[112:115], v[154:157], v[0:15]
	ds_read_b64_tr_b16 v[112:113], v210 offset:63488
	ds_read_b64_tr_b16 v[114:115], v210 offset:64000
	ds_read_b128 v[178:181], v120 offset:4096
	v_exp_f32_e32 v64, v64
	v_exp_f32_e32 v65, v65
	s_waitcnt lgkmcnt(7)
	v_mfma_f32_32x32x16_bf16 v[48:63], v[116:119], v[150:153], v[48:63]
	v_add_u32_e32 v120, s25, v205
	ds_read_b64_tr_b16 v[116:117], v210 offset:52224
	ds_read_b64_tr_b16 v[118:119], v210 offset:52736
	ds_read_b128 v[174:177], v120
	v_exp_f32_e32 v66, v66
	v_exp_f32_e32 v67, v67
	v_mfma_f32_32x32x16_bf16 v[32:47], v[104:107], v[150:153], v[32:47]
	ds_read_b64_tr_b16 v[104:105], v210 offset:56320
	ds_read_b64_tr_b16 v[106:107], v210 offset:56832
	ds_read_b128 v[170:173], v120 offset:4096
	v_exp_f32_e32 v68, v68
	v_exp_f32_e32 v69, v69
	s_waitcnt lgkmcnt(7)
	v_mfma_f32_32x32x16_bf16 v[16:31], v[108:111], v[150:153], v[16:31]
	s_add_i32 s44, s33, 3
	s_min_u32 s44, s44, s19
	s_mul_i32 s90, s44, 0x160000
	s_add_i32 s44, s10, s22
	s_mov_b32 m0, s44
	v_lshl_add_u64 v[212:213], v[200:201], 0, s[90:91]
	global_load_lds_dwordx4 v[212:213], off
	v_add_u32_e32 v120, s25, v206
	ds_read_b64_tr_b16 v[108:109], v210 offset:60416
	ds_read_b64_tr_b16 v[110:111], v210 offset:60928
	ds_read_b128 v[166:169], v120
	v_exp_f32_e32 v70, v70
	v_exp_f32_e32 v71, v71
	v_mfma_f32_32x32x16_bf16 v[0:15], v[112:115], v[150:153], v[0:15]
	ds_read_b64_tr_b16 v[112:113], v210 offset:64512
	ds_read_b64_tr_b16 v[114:115], v210 offset:65024
	ds_read_b128 v[162:165], v120 offset:4096
	v_exp_f32_e32 v72, v72
	v_exp_f32_e32 v73, v73
	s_waitcnt lgkmcnt(7)
	v_mfma_f32_32x32x16_bf16 v[48:63], v[116:119], v[146:149], v[48:63]
	v_exp_f32_e32 v74, v74
	v_exp_f32_e32 v75, v75
	v_mfma_f32_32x32x16_bf16 v[32:47], v[104:107], v[146:149], v[32:47]
	v_exp_f32_e32 v76, v76
	v_exp_f32_e32 v77, v77
	s_waitcnt lgkmcnt(1)
	v_mfma_f32_32x32x16_bf16 v[16:31], v[108:111], v[146:149], v[16:31]
	s_addk_i32 s44, 0x400
	s_mov_b32 m0, s44
	v_lshl_add_u64 v[212:213], v[212:213], 0, s[26:27]
	global_load_lds_dwordx4 v[212:213], off
	v_exp_f32_e32 v78, v78
	v_exp_f32_e32 v79, v79
	v_mfma_f32_32x32x16_bf16 v[0:15], v[112:115], v[146:149], v[0:15]
	s_waitcnt vmcnt(4) lgkmcnt(0)
	s_barrier
	s_cmp_ge_u32 s24, s4
	s_mov_b32 s20, s11
	s_mov_b32 s11, s23
	s_mov_b32 s33, s24
	s_cbranch_scc0 .LBB0_86
	ds_bpermute_b32 v64, v246, v209
	s_waitcnt vmcnt(0)
	s_barrier
	s_cmpk_lt_u32 s17, 0x100
	s_mov_b64 s[10:11], -1
	s_waitcnt lgkmcnt(0)
	v_add_f32_e32 v64, v209, v64
	v_div_scale_f32 v65, s[4:5], v64, v64, 1.0
	v_rcp_f32_e32 v66, v65
	v_div_scale_f32 v67, vcc, 1.0, v64, 1.0
	s_cselect_b64 s[4:5], -1, 0
	v_fma_f32 v68, -v65, v66, 1.0
	v_fmac_f32_e32 v66, v68, v66
	v_mul_f32_e32 v68, v67, v66
	v_fma_f32 v69, -v65, v68, v67
	v_fmac_f32_e32 v68, v69, v66
	v_fma_f32 v65, -v65, v68, v67
	v_div_fmas_f32 v65, v65, v66, v68
	v_div_fixup_f32 v134, v65, v64, 1.0
	s_and_b64 vcc, exec, s[4:5]
	s_cbranch_vccnz .LBB0_89
	s_lshl_b32 s10, s18, 14
	s_add_i32 s10, s10, 0
	v_mul_f32_e32 v64, v48, v134
	v_lshl_add_u32 v65, v202, 2, s10
	v_mul_f32_e32 v66, v49, v134
	ds_write2st64_b32 v65, v64, v66 offset1:1
	v_mul_f32_e32 v64, v50, v134
	v_mul_f32_e32 v66, v51, v134
	ds_write2st64_b32 v65, v64, v66 offset0:2 offset1:3
	v_mul_f32_e32 v64, v52, v134
	v_mul_f32_e32 v66, v53, v134
	ds_write2st64_b32 v65, v64, v66 offset0:4 offset1:5
	v_mul_f32_e32 v64, v54, v134
	v_mul_f32_e32 v66, v55, v134
	ds_write2st64_b32 v65, v64, v66 offset0:6 offset1:7
	v_mul_f32_e32 v64, v56, v134
	v_mul_f32_e32 v66, v57, v134
	ds_write2st64_b32 v65, v64, v66 offset0:8 offset1:9
	v_mul_f32_e32 v64, v58, v134
	v_mul_f32_e32 v66, v59, v134
	ds_write2st64_b32 v65, v64, v66 offset0:10 offset1:11
	v_mul_f32_e32 v64, v60, v134
	v_mul_f32_e32 v66, v61, v134
	ds_write2st64_b32 v65, v64, v66 offset0:12 offset1:13
	v_mul_f32_e32 v64, v62, v134
	v_mul_f32_e32 v66, v63, v134
	ds_write2st64_b32 v65, v64, v66 offset0:14 offset1:15
	v_mul_f32_e32 v64, v32, v134
	v_mul_f32_e32 v66, v33, v134
	ds_write2st64_b32 v65, v64, v66 offset0:16 offset1:17
	v_mul_f32_e32 v64, v34, v134
	v_mul_f32_e32 v66, v35, v134
	ds_write2st64_b32 v65, v64, v66 offset0:18 offset1:19
	v_mul_f32_e32 v64, v36, v134
	v_mul_f32_e32 v66, v37, v134
	ds_write2st64_b32 v65, v64, v66 offset0:20 offset1:21
	v_mul_f32_e32 v64, v38, v134
	v_mul_f32_e32 v66, v39, v134
	ds_write2st64_b32 v65, v64, v66 offset0:22 offset1:23
	v_mul_f32_e32 v64, v40, v134
	v_mul_f32_e32 v66, v41, v134
	ds_write2st64_b32 v65, v64, v66 offset0:24 offset1:25
	v_mul_f32_e32 v64, v42, v134
	v_mul_f32_e32 v66, v43, v134
	ds_write2st64_b32 v65, v64, v66 offset0:26 offset1:27
	v_mul_f32_e32 v64, v44, v134
	v_mul_f32_e32 v66, v45, v134
	ds_write2st64_b32 v65, v64, v66 offset0:28 offset1:29
	v_mul_f32_e32 v64, v46, v134
	v_mul_f32_e32 v66, v47, v134
	ds_write2st64_b32 v65, v64, v66 offset0:30 offset1:31
	v_mul_f32_e32 v64, v16, v134
	v_mul_f32_e32 v66, v17, v134
	ds_write2st64_b32 v65, v64, v66 offset0:32 offset1:33
	v_mul_f32_e32 v64, v18, v134
	v_mul_f32_e32 v66, v19, v134
	ds_write2st64_b32 v65, v64, v66 offset0:34 offset1:35
	v_mul_f32_e32 v64, v20, v134
	v_mul_f32_e32 v66, v21, v134
	ds_write2st64_b32 v65, v64, v66 offset0:36 offset1:37
	v_mul_f32_e32 v64, v22, v134
	v_mul_f32_e32 v66, v23, v134
	ds_write2st64_b32 v65, v64, v66 offset0:38 offset1:39
	v_mul_f32_e32 v64, v24, v134
	v_mul_f32_e32 v66, v25, v134
	ds_write2st64_b32 v65, v64, v66 offset0:40 offset1:41
	v_mul_f32_e32 v64, v26, v134
	v_mul_f32_e32 v66, v27, v134
	ds_write2st64_b32 v65, v64, v66 offset0:42 offset1:43
	v_mul_f32_e32 v64, v28, v134
	v_mul_f32_e32 v66, v29, v134
	ds_write2st64_b32 v65, v64, v66 offset0:44 offset1:45
	v_mul_f32_e32 v64, v30, v134
	v_mul_f32_e32 v66, v31, v134
	ds_write2st64_b32 v65, v64, v66 offset0:46 offset1:47
	v_mul_f32_e32 v64, v0, v134
	v_mul_f32_e32 v66, v1, v134
	ds_write2st64_b32 v65, v64, v66 offset0:48 offset1:49
	v_mul_f32_e32 v64, v2, v134
	v_mul_f32_e32 v66, v3, v134
	ds_write2st64_b32 v65, v64, v66 offset0:50 offset1:51
	v_mul_f32_e32 v64, v4, v134
	v_mul_f32_e32 v66, v5, v134
	ds_write2st64_b32 v65, v64, v66 offset0:52 offset1:53
	v_mul_f32_e32 v64, v6, v134
	v_mul_f32_e32 v66, v7, v134
	ds_write2st64_b32 v65, v64, v66 offset0:54 offset1:55
	v_mul_f32_e32 v64, v8, v134
	v_mul_f32_e32 v66, v9, v134
	ds_write2st64_b32 v65, v64, v66 offset0:56 offset1:57
	v_mul_f32_e32 v64, v10, v134
	v_mul_f32_e32 v66, v11, v134
	ds_write2st64_b32 v65, v64, v66 offset0:58 offset1:59
	v_mul_f32_e32 v64, v12, v134
	v_mul_f32_e32 v66, v13, v134
	ds_write2st64_b32 v65, v64, v66 offset0:60 offset1:61
	v_mul_f32_e32 v64, v14, v134
	v_mul_f32_e32 v66, v15, v134
	s_mov_b64 s[10:11], 0
	ds_write2st64_b32 v65, v64, v66 offset0:62 offset1:63
